# combo + out-proj tile store loop rewritten (16 LDS reads in flight)
# baseline (speedup 1.0000x reference)
; DI void outproj_item(const Params& p, int l, int it, char* lds) {
;     ...
; #pragma unroll 4
;   for (int i = 0; i < 16; ++i) {
;     const int c = tid + 256 * i, tl = c >> 5, ch = c & 31;
;     const u32x4 v = *(const u32x4*)(lds + tl * RS + ch * 16);
;     *(u32x4*)(outb + ((size_t)mt * 128 + tl) * 1024 + nt * 256 + ch * 8) = v;
;   }
.LBB0_540:
	v_ashrrev_i32_e32 v6, 5, v181
	v_mad_u32_u24 v8, v6, s73, v178
	v_add_u32_e32 v6, s80, v6
	v_mov_b32_e32 v7, 0
	v_lshlrev_b64 v[6:7], 11, v[6:7]
	v_lshl_add_u64 v[6:7], v[0:1], 0, v[6:7]
	s_mov_b64 s[2:3], 0x4000
	ds_read_b128 v[12:15], v8
	ds_read_b128 v[16:19], v8 offset:4224
	ds_read_b128 v[20:23], v8 offset:8448
	ds_read_b128 v[24:27], v8 offset:12672
	ds_read_b128 v[28:31], v8 offset:16896
	ds_read_b128 v[32:35], v8 offset:21120
	ds_read_b128 v[36:39], v8 offset:25344
	ds_read_b128 v[40:43], v8 offset:29568
	ds_read_b128 v[44:47], v8 offset:33792
	ds_read_b128 v[48:51], v8 offset:38016
	ds_read_b128 v[52:55], v8 offset:42240
	ds_read_b128 v[56:59], v8 offset:46464
	ds_read_b128 v[60:63], v8 offset:50688
	ds_read_b128 v[64:67], v8 offset:54912
	ds_read_b128 v[68:71], v8 offset:59136
	ds_read_b128 v[72:75], v8 offset:63360
	s_waitcnt lgkmcnt(15)
	global_store_dwordx4 v[6:7], v[12:15], off
	v_lshl_add_u64 v[6:7], v[6:7], 0, s[2:3]
	s_waitcnt lgkmcnt(14)
	global_store_dwordx4 v[6:7], v[16:19], off
	v_lshl_add_u64 v[6:7], v[6:7], 0, s[2:3]
	s_waitcnt lgkmcnt(13)
	global_store_dwordx4 v[6:7], v[20:23], off
	v_lshl_add_u64 v[6:7], v[6:7], 0, s[2:3]
	s_waitcnt lgkmcnt(12)
	global_store_dwordx4 v[6:7], v[24:27], off
	v_lshl_add_u64 v[6:7], v[6:7], 0, s[2:3]
	s_waitcnt lgkmcnt(11)
	global_store_dwordx4 v[6:7], v[28:31], off
	v_lshl_add_u64 v[6:7], v[6:7], 0, s[2:3]
	s_waitcnt lgkmcnt(10)
	global_store_dwordx4 v[6:7], v[32:35], off
	v_lshl_add_u64 v[6:7], v[6:7], 0, s[2:3]
	s_waitcnt lgkmcnt(9)
	global_store_dwordx4 v[6:7], v[36:39], off
	v_lshl_add_u64 v[6:7], v[6:7], 0, s[2:3]
	s_waitcnt lgkmcnt(8)
	global_store_dwordx4 v[6:7], v[40:43], off
	v_lshl_add_u64 v[6:7], v[6:7], 0, s[2:3]
	s_waitcnt lgkmcnt(7)
	global_store_dwordx4 v[6:7], v[44:47], off
	v_lshl_add_u64 v[6:7], v[6:7], 0, s[2:3]
	s_waitcnt lgkmcnt(6)
	global_store_dwordx4 v[6:7], v[48:51], off
	v_lshl_add_u64 v[6:7], v[6:7], 0, s[2:3]
	s_waitcnt lgkmcnt(5)
	global_store_dwordx4 v[6:7], v[52:55], off
	v_lshl_add_u64 v[6:7], v[6:7], 0, s[2:3]
	s_waitcnt lgkmcnt(4)
	global_store_dwordx4 v[6:7], v[56:59], off
	v_lshl_add_u64 v[6:7], v[6:7], 0, s[2:3]
	s_waitcnt lgkmcnt(3)
	global_store_dwordx4 v[6:7], v[60:63], off
	v_lshl_add_u64 v[6:7], v[6:7], 0, s[2:3]
	s_waitcnt lgkmcnt(2)
	global_store_dwordx4 v[6:7], v[64:67], off
	v_lshl_add_u64 v[6:7], v[6:7], 0, s[2:3]
	s_waitcnt lgkmcnt(1)
	global_store_dwordx4 v[6:7], v[68:71], off
	v_lshl_add_u64 v[6:7], v[6:7], 0, s[2:3]
	s_waitcnt lgkmcnt(0)
	global_store_dwordx4 v[6:7], v[72:75], off
	s_add_i32 s27, s27, s68
	s_cmpk_gt_i32 s27, 0x1ff
	s_cbranch_scc0 .LBB0_533
